# GEMM K-loop: trailing SALU/VALU moved out of compute segments, loop-top lgkm wait hoisted, 8 s_nop removed by reordering M0 writes
# baseline (speedup 1.0000x reference)
.LBB0_385:
	s_add_i32 s43, s6, -2
	s_add_u32 s0, s46, 0x80
	s_addc_u32 s1, s47, 0
	s_add_u32 s48, s44, 0x100
	v_mov_b32_e32 v2, 0
	s_addc_u32 s49, s45, 0
	s_mov_b32 s44, 0
	v_mov_b32_e32 v3, v2
	v_mov_b32_e32 v4, v2
	v_mov_b32_e32 v5, v2
	v_mov_b32_e32 v6, v2
	v_mov_b32_e32 v7, v2
	v_mov_b32_e32 v8, v2
	v_mov_b32_e32 v9, v2
	s_waitcnt vmcnt(0)
	v_mov_b32_e32 v18, v2
	v_mov_b32_e32 v19, v2
	v_mov_b32_e32 v20, v2
	v_mov_b32_e32 v21, v2
	v_mov_b32_e32 v22, v2
	v_mov_b32_e32 v23, v2
	v_mov_b32_e32 v24, v2
	v_mov_b32_e32 v25, v2
	v_mov_b32_e32 v34, v2
	v_mov_b32_e32 v35, v2
	v_mov_b32_e32 v36, v2
	v_mov_b32_e32 v37, v2
	v_mov_b32_e32 v38, v2
	v_mov_b32_e32 v39, v2
	v_mov_b32_e32 v40, v2
	v_mov_b32_e32 v41, v2
	v_mov_b32_e32 v50, v2
	v_mov_b32_e32 v51, v2
	v_mov_b32_e32 v52, v2
	v_mov_b32_e32 v53, v2
	v_mov_b32_e32 v54, v2
	v_mov_b32_e32 v55, v2
	v_mov_b32_e32 v56, v2
	v_mov_b32_e32 v57, v2
	v_mov_b32_e32 v10, v2
	v_mov_b32_e32 v11, v2
	v_mov_b32_e32 v12, v2
	v_mov_b32_e32 v13, v2
	v_mov_b32_e32 v14, v2
	v_mov_b32_e32 v15, v2
	v_mov_b32_e32 v16, v2
	v_mov_b32_e32 v17, v2
	v_mov_b32_e32 v26, v2
	v_mov_b32_e32 v27, v2
	v_mov_b32_e32 v28, v2
	v_mov_b32_e32 v29, v2
	v_mov_b32_e32 v30, v2
	v_mov_b32_e32 v31, v2
	v_mov_b32_e32 v32, v2
	v_mov_b32_e32 v33, v2
	v_mov_b32_e32 v42, v2
	v_mov_b32_e32 v43, v2
	v_mov_b32_e32 v44, v2
	v_mov_b32_e32 v45, v2
	v_mov_b32_e32 v46, v2
	v_mov_b32_e32 v47, v2
	v_mov_b32_e32 v48, v2
	v_mov_b32_e32 v49, v2
	v_mov_b32_e32 v58, v2
	v_mov_b32_e32 v59, v2
	v_mov_b32_e32 v60, v2
	v_mov_b32_e32 v61, v2
	v_mov_b32_e32 v62, v2
	v_mov_b32_e32 v63, v2
	v_mov_b32_e32 v64, v2
	v_mov_b32_e32 v65, v2
	v_mov_b32_e32 v66, v2
	v_mov_b32_e32 v67, v2
	v_mov_b32_e32 v68, v2
	v_mov_b32_e32 v69, v2
	v_mov_b32_e32 v70, v2
	v_mov_b32_e32 v71, v2
	v_mov_b32_e32 v72, v2
	v_mov_b32_e32 v73, v2
	v_mov_b32_e32 v82, v2
	v_mov_b32_e32 v83, v2
	s_waitcnt vmcnt(0)
	v_mov_b32_e32 v84, v2
	v_mov_b32_e32 v85, v2
	v_mov_b32_e32 v86, v2
	v_mov_b32_e32 v87, v2
	v_mov_b32_e32 v88, v2
	v_mov_b32_e32 v89, v2
	v_mov_b32_e32 v98, v2
	v_mov_b32_e32 v99, v2
	v_mov_b32_e32 v100, v2
	v_mov_b32_e32 v101, v2
	v_mov_b32_e32 v102, v2
	v_mov_b32_e32 v103, v2
	v_mov_b32_e32 v104, v2
	v_mov_b32_e32 v105, v2
	v_mov_b32_e32 v114, v2
	v_mov_b32_e32 v115, v2
	v_mov_b32_e32 v116, v2
	v_mov_b32_e32 v117, v2
	v_mov_b32_e32 v118, v2
	v_mov_b32_e32 v119, v2
	v_mov_b32_e32 v120, v2
	v_mov_b32_e32 v121, v2
	v_mov_b32_e32 v74, v2
	v_mov_b32_e32 v75, v2
	v_mov_b32_e32 v76, v2
	v_mov_b32_e32 v77, v2
	v_mov_b32_e32 v78, v2
	v_mov_b32_e32 v79, v2
	v_mov_b32_e32 v80, v2
	v_mov_b32_e32 v81, v2
	v_mov_b32_e32 v90, v2
	v_mov_b32_e32 v91, v2
	v_mov_b32_e32 v92, v2
	v_mov_b32_e32 v93, v2
	v_mov_b32_e32 v94, v2
	v_mov_b32_e32 v95, v2
	v_mov_b32_e32 v96, v2
	v_mov_b32_e32 v97, v2
	v_mov_b32_e32 v106, v2
	v_mov_b32_e32 v107, v2
	v_mov_b32_e32 v108, v2
	v_mov_b32_e32 v109, v2
	v_mov_b32_e32 v110, v2
	v_mov_b32_e32 v111, v2
	v_mov_b32_e32 v112, v2
	v_mov_b32_e32 v113, v2
	v_mov_b32_e32 v122, v2
	v_mov_b32_e32 v123, v2
	v_mov_b32_e32 v124, v2
	v_mov_b32_e32 v125, v2
	v_mov_b32_e32 v126, v2
	v_mov_b32_e32 v127, v2
	v_mov_b32_e32 v128, v2
	v_mov_b32_e32 v129, v2
	s_waitcnt lgkmcnt(0)
.LBB0_386:
	s_add_i32 s71, s44, 2
	s_add_u32 s46, s0, 0x80
	s_addc_u32 s45, s1, 0
	s_add_i32 vcc_lo, 0, 0x10000
	v_add_u32_e32 v0, vcc_lo, v224
	ds_read_b128 v[130:133], v0
	ds_read_b128 v[134:137], v0 offset:1024
	ds_read_b128 v[138:141], v0 offset:2048
	ds_read_b128 v[142:145], v0 offset:3072
	s_cmp_eq_u32 s43, s44
	s_cselect_b32 s44, s72, s46
	s_cselect_b32 s45, s73, s45
	s_cselect_b32 s47, s75, s49
	s_cselect_b32 s46, s74, s48
	v_lshl_add_u64 v[200:201], s[0:1], 0, v[172:173]
	s_add_i32 m0, s98, 0xc000
	ds_read_b128 v[146:149], v229
	ds_read_b128 v[150:153], v229 offset:1024
	ds_read_b128 v[176:179], v229 offset:2048
	ds_read_b128 v[180:183], v229 offset:3072
	ds_read_b128 v[184:187], v229 offset:4096
	ds_read_b128 v[188:191], v229 offset:5120
	ds_read_b128 v[192:195], v229 offset:6144
	ds_read_b128 v[196:199], v229 offset:7168
	global_load_lds_dwordx4 v[200:201], off
	s_add_i32 m0, s98, 0xe000
	v_lshl_add_u64 v[200:201], s[0:1], 0, v[174:175]
	global_load_lds_dwordx4 v[200:201], off
	s_waitcnt lgkmcnt(8)
	s_barrier
	s_waitcnt lgkmcnt(0)
	v_mfma_f32_16x16x32_bf16 v[126:129], v[130:133], v[146:149], v[126:129]
	v_mfma_f32_16x16x32_bf16 v[122:125], v[138:141], v[146:149], v[122:125]
	v_mfma_f32_16x16x32_bf16 v[110:113], v[130:133], v[176:179], v[110:113]
	v_mfma_f32_16x16x32_bf16 v[106:109], v[138:141], v[176:179], v[106:109]
	v_mfma_f32_16x16x32_bf16 v[94:97], v[130:133], v[184:187], v[94:97]
	v_mfma_f32_16x16x32_bf16 v[90:93], v[138:141], v[184:187], v[90:93]
	v_mfma_f32_16x16x32_bf16 v[78:81], v[130:133], v[192:195], v[78:81]
	v_mfma_f32_16x16x32_bf16 v[74:77], v[138:141], v[192:195], v[74:77]
	v_mfma_f32_16x16x32_bf16 v[126:129], v[134:137], v[150:153], v[126:129]
	v_mfma_f32_16x16x32_bf16 v[122:125], v[142:145], v[150:153], v[122:125]
	v_mfma_f32_16x16x32_bf16 v[110:113], v[134:137], v[180:183], v[110:113]
	v_mfma_f32_16x16x32_bf16 v[106:109], v[142:145], v[180:183], v[106:109]
	v_mfma_f32_16x16x32_bf16 v[94:97], v[134:137], v[188:191], v[94:97]
	v_mfma_f32_16x16x32_bf16 v[90:93], v[142:145], v[188:191], v[90:93]
	v_mfma_f32_16x16x32_bf16 v[78:81], v[134:137], v[196:199], v[78:81]
	v_mfma_f32_16x16x32_bf16 v[74:77], v[142:145], v[196:199], v[74:77]
	s_barrier
	s_add_i32 vcc_hi, 0, 0x14000
	s_add_i32 vcc_lo, vcc_lo, s97
	v_add_u32_e32 v0, vcc_hi, v224
	v_lshl_add_u64 v[204:205], s[46:47], 0, v[158:159]
	s_mov_b32 m0, vcc_lo
	ds_read_b128 v[200:203], v0
	ds_read_b128 v[230:233], v0 offset:1024
	ds_read_b128 v[234:237], v0 offset:2048
	ds_read_b128 v[238:241], v0 offset:3072
	global_load_lds_dwordx4 v[204:205], off
	s_add_i32 m0, vcc_lo, 0x2000
	v_lshl_add_u64 v[242:243], s[46:47], 0, v[162:163]
	global_load_lds_dwordx4 v[242:243], off
	s_barrier
	s_waitcnt lgkmcnt(0)
	v_mfma_f32_16x16x32_bf16 v[118:121], v[200:203], v[146:149], v[118:121]
	v_mfma_f32_16x16x32_bf16 v[114:117], v[234:237], v[146:149], v[114:117]
	v_mfma_f32_16x16x32_bf16 v[102:105], v[200:203], v[176:179], v[102:105]
	v_mfma_f32_16x16x32_bf16 v[98:101], v[234:237], v[176:179], v[98:101]
	v_mfma_f32_16x16x32_bf16 v[86:89], v[200:203], v[184:187], v[86:89]
	v_mfma_f32_16x16x32_bf16 v[82:85], v[234:237], v[184:187], v[82:85]
	v_mfma_f32_16x16x32_bf16 v[70:73], v[200:203], v[192:195], v[70:73]
	v_mfma_f32_16x16x32_bf16 v[66:69], v[234:237], v[192:195], v[66:69]
	v_mfma_f32_16x16x32_bf16 v[118:121], v[230:233], v[150:153], v[118:121]
	v_mfma_f32_16x16x32_bf16 v[114:117], v[238:241], v[150:153], v[114:117]
	v_mfma_f32_16x16x32_bf16 v[102:105], v[230:233], v[180:183], v[102:105]
	v_mfma_f32_16x16x32_bf16 v[98:101], v[238:241], v[180:183], v[98:101]
	v_mfma_f32_16x16x32_bf16 v[86:89], v[230:233], v[188:191], v[86:89]
	v_mfma_f32_16x16x32_bf16 v[82:85], v[238:241], v[188:191], v[82:85]
	v_mfma_f32_16x16x32_bf16 v[70:73], v[230:233], v[196:199], v[70:73]
	v_mfma_f32_16x16x32_bf16 v[66:69], v[238:241], v[196:199], v[66:69]
	s_barrier
	s_mov_b32 m0, s98
	v_lshl_add_u64 v[244:245], s[44:45], 0, v[156:157]
	ds_read_b128 v[146:149], v229 offset:16384
	ds_read_b128 v[150:153], v229 offset:17408
	ds_read_b128 v[176:179], v229 offset:18432
	ds_read_b128 v[180:183], v229 offset:19456
	ds_read_b128 v[184:187], v229 offset:20480
	ds_read_b128 v[188:191], v229 offset:21504
	ds_read_b128 v[192:195], v229 offset:22528
	ds_read_b128 v[196:199], v229 offset:23552
	global_load_lds_dwordx4 v[244:245], off
	s_mov_b32 m0, s99
	v_lshl_add_u64 v[246:247], s[44:45], 0, v[160:161]
	global_load_lds_dwordx4 v[246:247], off
	s_barrier
	s_waitcnt lgkmcnt(0)
	v_mfma_f32_16x16x32_bf16 v[62:65], v[130:133], v[146:149], v[62:65]
	v_mfma_f32_16x16x32_bf16 v[58:61], v[138:141], v[146:149], v[58:61]
	v_mfma_f32_16x16x32_bf16 v[46:49], v[130:133], v[176:179], v[46:49]
	v_mfma_f32_16x16x32_bf16 v[42:45], v[138:141], v[176:179], v[42:45]
	v_mfma_f32_16x16x32_bf16 v[30:33], v[130:133], v[184:187], v[30:33]
	v_mfma_f32_16x16x32_bf16 v[26:29], v[138:141], v[184:187], v[26:29]
	v_mfma_f32_16x16x32_bf16 v[14:17], v[130:133], v[192:195], v[14:17]
	v_mfma_f32_16x16x32_bf16 v[10:13], v[138:141], v[192:195], v[10:13]
	v_mfma_f32_16x16x32_bf16 v[62:65], v[134:137], v[150:153], v[62:65]
	v_mfma_f32_16x16x32_bf16 v[58:61], v[142:145], v[150:153], v[58:61]
	v_mfma_f32_16x16x32_bf16 v[46:49], v[134:137], v[180:183], v[46:49]
	v_mfma_f32_16x16x32_bf16 v[42:45], v[142:145], v[180:183], v[42:45]
	v_mfma_f32_16x16x32_bf16 v[30:33], v[134:137], v[188:191], v[30:33]
	v_mfma_f32_16x16x32_bf16 v[26:29], v[142:145], v[188:191], v[26:29]
	v_mfma_f32_16x16x32_bf16 v[14:17], v[134:137], v[196:199], v[14:17]
	v_mfma_f32_16x16x32_bf16 v[10:13], v[142:145], v[196:199], v[10:13]
	s_barrier
	s_add_u32 s46, s46, s95
	s_addc_u32 s47, s47, 0
	s_add_i32 vcc_lo, vcc_hi, s97
	v_lshl_add_u64 v[248:249], s[46:47], 0, v[158:159]
	s_mov_b32 m0, vcc_lo
	v_lshl_add_u64 v[250:251], s[46:47], 0, v[162:163]
	global_load_lds_dwordx4 v[248:249], off
	s_add_i32 m0, vcc_lo, 0x2000
	s_nop 0
	global_load_lds_dwordx4 v[250:251], off
	s_waitcnt vmcnt(6)
	s_barrier
	v_mfma_f32_16x16x32_bf16 v[54:57], v[200:203], v[146:149], v[54:57]
	v_mfma_f32_16x16x32_bf16 v[50:53], v[234:237], v[146:149], v[50:53]
	v_mfma_f32_16x16x32_bf16 v[38:41], v[200:203], v[176:179], v[38:41]
	v_mfma_f32_16x16x32_bf16 v[34:37], v[234:237], v[176:179], v[34:37]
	v_mfma_f32_16x16x32_bf16 v[22:25], v[200:203], v[184:187], v[22:25]
	v_mfma_f32_16x16x32_bf16 v[18:21], v[234:237], v[184:187], v[18:21]
	v_mfma_f32_16x16x32_bf16 v[6:9], v[200:203], v[192:195], v[6:9]
	v_mfma_f32_16x16x32_bf16 v[2:5], v[234:237], v[192:195], v[2:5]
	v_mfma_f32_16x16x32_bf16 v[54:57], v[230:233], v[150:153], v[54:57]
	v_mfma_f32_16x16x32_bf16 v[50:53], v[238:241], v[150:153], v[50:53]
	v_mfma_f32_16x16x32_bf16 v[38:41], v[230:233], v[180:183], v[38:41]
	v_mfma_f32_16x16x32_bf16 v[34:37], v[238:241], v[180:183], v[34:37]
	v_mfma_f32_16x16x32_bf16 v[22:25], v[230:233], v[188:191], v[22:25]
	v_mfma_f32_16x16x32_bf16 v[18:21], v[238:241], v[188:191], v[18:21]
	v_mfma_f32_16x16x32_bf16 v[6:9], v[230:233], v[196:199], v[6:9]
	v_mfma_f32_16x16x32_bf16 v[2:5], v[238:241], v[196:199], v[2:5]
	s_barrier
	s_add_i32 s46, 0, 0x18000
	v_add_u32_e32 v0, s46, v224
	ds_read_b128 v[130:133], v0
	ds_read_b128 v[134:137], v0 offset:1024
	ds_read_b128 v[138:141], v0 offset:2048
	ds_read_b128 v[142:145], v0 offset:3072
	s_add_u32 s44, s44, s20
	s_addc_u32 s45, s45, 0
	s_mov_b32 m0, s94
	v_lshl_add_u64 v[200:201], s[44:45], 0, v[156:157]
	ds_read_b128 v[146:149], v229 offset:32768
	ds_read_b128 v[150:153], v229 offset:33792
	ds_read_b128 v[176:179], v229 offset:34816
	ds_read_b128 v[180:183], v229 offset:35840
	ds_read_b128 v[184:187], v229 offset:36864
	ds_read_b128 v[188:191], v229 offset:37888
	ds_read_b128 v[192:195], v229 offset:38912
	ds_read_b128 v[196:199], v229 offset:39936
	global_load_lds_dwordx4 v[200:201], off
	s_mov_b32 m0, s65
	v_lshl_add_u64 v[200:201], s[44:45], 0, v[160:161]
	global_load_lds_dwordx4 v[200:201], off
	s_waitcnt lgkmcnt(8)
	s_barrier
	s_waitcnt lgkmcnt(0)
	v_mfma_f32_16x16x32_bf16 v[126:129], v[130:133], v[146:149], v[126:129]
	v_mfma_f32_16x16x32_bf16 v[122:125], v[138:141], v[146:149], v[122:125]
	v_mfma_f32_16x16x32_bf16 v[110:113], v[130:133], v[176:179], v[110:113]
	v_mfma_f32_16x16x32_bf16 v[106:109], v[138:141], v[176:179], v[106:109]
	v_mfma_f32_16x16x32_bf16 v[94:97], v[130:133], v[184:187], v[94:97]
	v_mfma_f32_16x16x32_bf16 v[90:93], v[138:141], v[184:187], v[90:93]
	v_mfma_f32_16x16x32_bf16 v[78:81], v[130:133], v[192:195], v[78:81]
	v_mfma_f32_16x16x32_bf16 v[74:77], v[138:141], v[192:195], v[74:77]
	v_mfma_f32_16x16x32_bf16 v[126:129], v[134:137], v[150:153], v[126:129]
	v_mfma_f32_16x16x32_bf16 v[122:125], v[142:145], v[150:153], v[122:125]
	v_mfma_f32_16x16x32_bf16 v[110:113], v[134:137], v[180:183], v[110:113]
	v_mfma_f32_16x16x32_bf16 v[106:109], v[142:145], v[180:183], v[106:109]
	v_mfma_f32_16x16x32_bf16 v[94:97], v[134:137], v[188:191], v[94:97]
	v_mfma_f32_16x16x32_bf16 v[90:93], v[142:145], v[188:191], v[90:93]
	v_mfma_f32_16x16x32_bf16 v[78:81], v[134:137], v[196:199], v[78:81]
	v_mfma_f32_16x16x32_bf16 v[74:77], v[142:145], v[196:199], v[74:77]
	s_barrier
	s_add_i32 s44, 0, 0x1c000
	s_add_i32 s45, s46, s97
	v_add_u32_e32 v0, s44, v224
	v_lshl_add_u64 v[204:205], v[204:205], 0, s[22:23]
	s_mov_b32 m0, s45
	ds_read_b128 v[200:203], v0
	ds_read_b128 v[230:233], v0 offset:1024
	ds_read_b128 v[234:237], v0 offset:2048
	ds_read_b128 v[238:241], v0 offset:3072
	global_load_lds_dwordx4 v[204:205], off
	s_add_i32 m0, s45, 0x2000
	v_lshl_add_u64 v[204:205], v[242:243], 0, s[22:23]
	global_load_lds_dwordx4 v[204:205], off
	s_barrier
	s_waitcnt lgkmcnt(0)
	v_mfma_f32_16x16x32_bf16 v[118:121], v[200:203], v[146:149], v[118:121]
	v_mfma_f32_16x16x32_bf16 v[114:117], v[234:237], v[146:149], v[114:117]
	v_mfma_f32_16x16x32_bf16 v[102:105], v[200:203], v[176:179], v[102:105]
	v_mfma_f32_16x16x32_bf16 v[98:101], v[234:237], v[176:179], v[98:101]
	v_mfma_f32_16x16x32_bf16 v[86:89], v[200:203], v[184:187], v[86:89]
	v_mfma_f32_16x16x32_bf16 v[82:85], v[234:237], v[184:187], v[82:85]
	v_mfma_f32_16x16x32_bf16 v[70:73], v[200:203], v[192:195], v[70:73]
	v_mfma_f32_16x16x32_bf16 v[66:69], v[234:237], v[192:195], v[66:69]
	v_mfma_f32_16x16x32_bf16 v[118:121], v[230:233], v[150:153], v[118:121]
	v_mfma_f32_16x16x32_bf16 v[114:117], v[238:241], v[150:153], v[114:117]
	v_mfma_f32_16x16x32_bf16 v[102:105], v[230:233], v[180:183], v[102:105]
	v_mfma_f32_16x16x32_bf16 v[98:101], v[238:241], v[180:183], v[98:101]
	v_mfma_f32_16x16x32_bf16 v[86:89], v[230:233], v[188:191], v[86:89]
	v_mfma_f32_16x16x32_bf16 v[82:85], v[238:241], v[188:191], v[82:85]
	v_mfma_f32_16x16x32_bf16 v[70:73], v[230:233], v[196:199], v[70:73]
	v_mfma_f32_16x16x32_bf16 v[66:69], v[238:241], v[196:199], v[66:69]
	s_barrier
	s_mov_b32 m0, s87
	v_lshl_add_u64 v[204:205], v[244:245], 0, s[22:23]
	ds_read_b128 v[146:149], v229 offset:49152
	ds_read_b128 v[150:153], v229 offset:50176
	ds_read_b128 v[176:179], v229 offset:51200
	ds_read_b128 v[180:183], v229 offset:52224
	ds_read_b128 v[184:187], v229 offset:53248
	ds_read_b128 v[188:191], v229 offset:54272
	ds_read_b128 v[192:195], v229 offset:55296
	ds_read_b128 v[196:199], v229 offset:56320
	global_load_lds_dwordx4 v[204:205], off
	s_mov_b32 m0, s29
	v_lshl_add_u64 v[204:205], v[246:247], 0, s[22:23]
	global_load_lds_dwordx4 v[204:205], off
	s_barrier
	s_waitcnt lgkmcnt(0)
	v_mfma_f32_16x16x32_bf16 v[62:65], v[130:133], v[146:149], v[62:65]
	v_mfma_f32_16x16x32_bf16 v[58:61], v[138:141], v[146:149], v[58:61]
	v_mfma_f32_16x16x32_bf16 v[46:49], v[130:133], v[176:179], v[46:49]
	v_mfma_f32_16x16x32_bf16 v[42:45], v[138:141], v[176:179], v[42:45]
	v_mfma_f32_16x16x32_bf16 v[30:33], v[130:133], v[184:187], v[30:33]
	v_mfma_f32_16x16x32_bf16 v[26:29], v[138:141], v[184:187], v[26:29]
	v_mfma_f32_16x16x32_bf16 v[14:17], v[130:133], v[192:195], v[14:17]
	v_mfma_f32_16x16x32_bf16 v[10:13], v[138:141], v[192:195], v[10:13]
	v_mfma_f32_16x16x32_bf16 v[62:65], v[134:137], v[150:153], v[62:65]
	v_mfma_f32_16x16x32_bf16 v[58:61], v[142:145], v[150:153], v[58:61]
	v_mfma_f32_16x16x32_bf16 v[46:49], v[134:137], v[180:183], v[46:49]
	v_mfma_f32_16x16x32_bf16 v[42:45], v[142:145], v[180:183], v[42:45]
	v_mfma_f32_16x16x32_bf16 v[30:33], v[134:137], v[188:191], v[30:33]
	v_mfma_f32_16x16x32_bf16 v[26:29], v[142:145], v[188:191], v[26:29]
	v_mfma_f32_16x16x32_bf16 v[14:17], v[134:137], v[196:199], v[14:17]
	v_mfma_f32_16x16x32_bf16 v[10:13], v[142:145], v[196:199], v[10:13]
	s_barrier
	s_add_i32 s44, s44, s97
	s_mov_b32 m0, s44
	v_lshl_add_u64 v[130:131], v[248:249], 0, s[22:23]
	global_load_lds_dwordx4 v[130:131], off
	s_add_i32 m0, s44, 0x2000
	v_lshl_add_u64 v[130:131], v[250:251], 0, s[22:23]
	global_load_lds_dwordx4 v[130:131], off
	s_add_u32 s0, s0, 0x100
	s_addc_u32 s1, s1, 0
	s_add_u32 s48, s48, 0x100
	s_addc_u32 s49, s49, 0
	s_cmp_ge_i32 s71, s6
	s_mov_b32 s44, s71
	s_waitcnt vmcnt(6)
	s_barrier
	v_mfma_f32_16x16x32_bf16 v[54:57], v[200:203], v[146:149], v[54:57]
	v_mfma_f32_16x16x32_bf16 v[50:53], v[234:237], v[146:149], v[50:53]
	v_mfma_f32_16x16x32_bf16 v[38:41], v[200:203], v[176:179], v[38:41]
	v_mfma_f32_16x16x32_bf16 v[34:37], v[234:237], v[176:179], v[34:37]
	v_mfma_f32_16x16x32_bf16 v[22:25], v[200:203], v[184:187], v[22:25]
	v_mfma_f32_16x16x32_bf16 v[18:21], v[234:237], v[184:187], v[18:21]
	v_mfma_f32_16x16x32_bf16 v[6:9], v[200:203], v[192:195], v[6:9]
	v_mfma_f32_16x16x32_bf16 v[2:5], v[234:237], v[192:195], v[2:5]
	v_mfma_f32_16x16x32_bf16 v[54:57], v[230:233], v[150:153], v[54:57]
	v_mfma_f32_16x16x32_bf16 v[50:53], v[238:241], v[150:153], v[50:53]
	v_mfma_f32_16x16x32_bf16 v[38:41], v[230:233], v[180:183], v[38:41]
	v_mfma_f32_16x16x32_bf16 v[34:37], v[238:241], v[180:183], v[34:37]
	v_mfma_f32_16x16x32_bf16 v[22:25], v[230:233], v[188:191], v[22:25]
	v_mfma_f32_16x16x32_bf16 v[18:21], v[238:241], v[188:191], v[18:21]
	v_mfma_f32_16x16x32_bf16 v[6:9], v[230:233], v[196:199], v[6:9]
	v_mfma_f32_16x16x32_bf16 v[2:5], v[238:241], v[196:199], v[2:5]
	s_barrier
	s_cbranch_scc0 .LBB0_386
	s_lshl_b32 s46, s77, 8
	s_cmp_lt_i32 s64, 1
	s_mov_b64 s[0:1], -1
	s_cbranch_scc1 .LBB0_403
